# accumulator bias splat via 9 moves instead of 23 in the stick-breaking prompt tile
# speedup vs baseline: 1.0009x; 1.0009x over previous
; #define LAS __attribute__((address_space(3)))
; DI float fexp2(float x) { return __builtin_amdgcn_exp2f(x); }
; DI float frcp(float x) { return __builtin_amdgcn_rcpf(x); }
; #define MFMA32(a, b, c) __builtin_amdgcn_mfma_f32_32x32x16_bf16((a), (b), (c), 0, 0, 0)
; DI void prompt_tile(const LAS unsigned char* kc, const LAS unsigned char* vc, const bf16x8 (&qf)[4], f32x16 (&accO)[2], float& carry, float bias2, int key0, int Q0, int r, int h2) {
;     ...
;     if (key0 < Q0 + 31) {
;         f32x16 sk[2];
; #pragma unroll
;         for (int kb = 0; kb < 2; ++kb) {
; #pragma unroll
;             for (int i = 0; i < 16; ++i) sk[kb][i] = bias2;
; #pragma unroll
;             for (int s = 0; s < 4; ++s) { const bf16x8 a = *(const LAS bf16x8*)(kc + (32 * kb + r) * (KLD * 2) + (16 * s + 8 * h2) * 2); sk[kb] = MFMA32(a, qf[s], sk[kb]); }
;         }
;         const bool need_mask = key0 + 63 >= Q0;
;         f32x2 kp[2][8];
; #pragma unroll
;         for (int kb = 0; kb < 2; ++kb)
; #pragma unroll
;             for (int pq = 0; pq < 8; ++pq) {
;                 f32x2 e2; e2.x = fexp2(sk[kb][2 * pq]); e2.y = fexp2(sk[kb][2 * pq + 1]);
;                 const f32x2 d2 = e2 + 1.0f;
;                 f32x2 k2; k2.x = frcp(d2.x); k2.y = frcp(d2.y);
;                 kp[kb][pq] = k2;
;             }
.LBB0_569:
	s_max_i32 s12, s75, 2
	s_lshl_b32 s12, s12, 6
	s_addk_i32 s12, 0xff80
	s_ashr_i32 s13, s12, 31
	s_lshl_b64 s[14:15], s[12:13], 10
	v_lshl_add_u64 v[4:5], v[208:209], 0, s[14:15]
	global_load_dwordx4 v[176:179], v[4:5], off
	v_lshl_add_u64 v[4:5], s[12:13], 1, v[210:211]
	global_load_dwordx4 v[180:183], v[4:5], off
	v_cndmask_b32_e64 v3, 0, 1, s[60:61]
	v_readlane_b32 s16, v243, 24
	v_cmp_ne_u32_e64 s[18:19], 1, v3
	s_andn2_b64 vcc, exec, s[60:61]
	v_readlane_b32 s17, v243, 25
	s_cbranch_vccnz .LBB0_576
	s_lshl_b32 s12, s75, 6
	s_add_i32 s13, s74, 31
	s_cmp_ge_i32 s12, s13
	s_cbranch_scc1 .LBB0_574
	s_mul_i32 s13, s2, 0x2400
	v_add3_u32 v3, v218, s13, v219
	ds_read_b128 v[224:227], v3
	ds_read_b128 v[228:231], v3 offset:32
	v_mov_b32_e32 v39, v38
	v_mov_b64_e32 v[40:41], v[38:39]
	v_mov_b64_e32 v[42:43], v[38:39]
	v_mov_b64_e32 v[44:45], v[38:39]
	v_mov_b64_e32 v[46:47], v[38:39]
	v_mov_b64_e32 v[48:49], v[38:39]
	v_mov_b64_e32 v[50:51], v[38:39]
	v_mov_b64_e32 v[52:53], v[38:39]
	v_mov_b64_e32 v[54:55], v[38:39]
	s_or_b32 s13, s12, 63
	s_cmp_lt_i32 s13, s74
	s_waitcnt lgkmcnt(1)
	v_mfma_f32_32x32x16_bf16 v[56:71], v[224:227], v[72:75], v[40:55]
	ds_read_b128 v[224:227], v3 offset:64
	s_waitcnt lgkmcnt(1)
	v_mfma_f32_32x32x16_bf16 v[56:71], v[228:231], v[84:87], v[56:71]
	s_waitcnt lgkmcnt(0)
	v_mfma_f32_32x32x16_bf16 v[56:71], v[224:227], v[80:83], v[56:71]
	ds_read_b128 v[224:227], v3 offset:96
	s_waitcnt lgkmcnt(0)
	v_mfma_f32_32x32x16_bf16 v[56:71], v[224:227], v[76:79], v[56:71]
	ds_read_b128 v[224:227], v3 offset:4608
	s_waitcnt lgkmcnt(0)
	v_mfma_f32_32x32x16_bf16 v[40:55], v[224:227], v[72:75], v[40:55]
	ds_read_b128 v[224:227], v3 offset:4640
	s_nop 7
	v_exp_f32_e32 v4, v56
	v_exp_f32_e32 v5, v57
	s_nop 0
	v_pk_add_f32 v[4:5], v[4:5], 1.0 op_sel_hi:[1,0]
	s_waitcnt lgkmcnt(0)
	v_mfma_f32_32x32x16_bf16 v[40:55], v[224:227], v[84:87], v[40:55]
	ds_read_b128 v[224:227], v3 offset:4672
	v_rcp_f32_e32 v56, v4
	v_rcp_f32_e32 v57, v5
	v_exp_f32_e32 v4, v58
	v_exp_f32_e32 v5, v59
	v_exp_f32_e32 v58, v60
	v_exp_f32_e32 v59, v61
	s_waitcnt lgkmcnt(0)
	v_mfma_f32_32x32x16_bf16 v[40:55], v[224:227], v[80:83], v[40:55]
	ds_read_b128 v[224:227], v3 offset:4704
	v_add_f32_e64 v58, v58, 1.0
	v_add_f32_e64 v59, v59, 1.0
	v_exp_f32_e32 v60, v66
	v_rcp_f32_e32 v216, v58
	v_rcp_f32_e32 v217, v59
	v_exp_f32_e32 v58, v62
	v_exp_f32_e32 v59, v63
	s_waitcnt lgkmcnt(0)
	v_mfma_f32_32x32x16_bf16 v[40:55], v[224:227], v[76:79], v[40:55]
	v_add_f32_e64 v58, v58, 1.0
	v_add_f32_e64 v59, v59, 1.0
	v_exp_f32_e32 v61, v67
	v_rcp_f32_e32 v62, v58
	v_rcp_f32_e32 v63, v59
	v_exp_f32_e32 v58, v64
	v_exp_f32_e32 v59, v65
	v_exp_f32_e32 v64, v68
	s_nop 3
	v_exp_f32_e32 v44, v44
	v_exp_f32_e32 v45, v45
	v_exp_f32_e32 v65, v69
	v_exp_f32_e32 v66, v70
	v_exp_f32_e32 v67, v71
	v_pk_add_f32 v[44:45], v[44:45], 1.0 op_sel_hi:[1,0]
	v_exp_f32_e32 v40, v40
	v_rcp_f32_e32 v68, v44
	v_rcp_f32_e32 v69, v45
	v_exp_f32_e32 v44, v46
	v_exp_f32_e32 v45, v47
	v_exp_f32_e32 v41, v41
	v_exp_f32_e32 v42, v42
	v_exp_f32_e32 v43, v43
	v_pk_add_f32 v[44:45], v[44:45], 1.0 op_sel_hi:[1,0]
	v_exp_f32_e32 v46, v50
	v_rcp_f32_e32 v70, v44
	v_rcp_f32_e32 v71, v45
	v_exp_f32_e32 v44, v48
	v_exp_f32_e32 v45, v49
	v_exp_f32_e32 v47, v51
	v_exp_f32_e32 v48, v52
	v_exp_f32_e32 v49, v53
	v_exp_f32_e32 v50, v54
	v_exp_f32_e32 v51, v55
	v_pk_add_f32 v[4:5], v[4:5], 1.0 op_sel_hi:[1,0]
	v_pk_add_f32 v[58:59], v[58:59], 1.0 op_sel_hi:[1,0]
	v_pk_add_f32 v[60:61], v[60:61], 1.0 op_sel_hi:[1,0]
	v_pk_add_f32 v[64:65], v[64:65], 1.0 op_sel_hi:[1,0]
	v_pk_add_f32 v[66:67], v[66:67], 1.0 op_sel_hi:[1,0]
	v_pk_add_f32 v[40:41], v[40:41], 1.0 op_sel_hi:[1,0]
	v_pk_add_f32 v[42:43], v[42:43], 1.0 op_sel_hi:[1,0]
	v_pk_add_f32 v[44:45], v[44:45], 1.0 op_sel_hi:[1,0]
	v_pk_add_f32 v[46:47], v[46:47], 1.0 op_sel_hi:[1,0]
	v_pk_add_f32 v[48:49], v[48:49], 1.0 op_sel_hi:[1,0]
	v_pk_add_f32 v[50:51], v[50:51], 1.0 op_sel_hi:[1,0]
	v_rcp_f32_e32 v4, v4
	v_rcp_f32_e32 v5, v5
	v_rcp_f32_e32 v58, v58
	v_rcp_f32_e32 v59, v59
	v_rcp_f32_e32 v60, v60
	v_rcp_f32_e32 v61, v61
	v_rcp_f32_e32 v64, v64
	v_rcp_f32_e32 v65, v65
	v_rcp_f32_e32 v66, v66
	v_rcp_f32_e32 v67, v67
	v_rcp_f32_e32 v40, v40
	v_rcp_f32_e32 v41, v41
	v_rcp_f32_e32 v42, v42
	v_rcp_f32_e32 v43, v43
	v_rcp_f32_e32 v44, v44
	v_rcp_f32_e32 v45, v45
	v_rcp_f32_e32 v46, v46
	v_rcp_f32_e32 v47, v47
	v_rcp_f32_e32 v48, v48
	v_rcp_f32_e32 v49, v49
	v_rcp_f32_e32 v50, v50
	v_rcp_f32_e32 v51, v51
	s_cbranch_scc1 .LBB0_573
; DI void prompt_tile(const LAS unsigned char* kc, const LAS unsigned char* vc, const bf16x8 (&qf)[4], f32x16 (&accO)[2], float& carry, float bias2, int key0, int Q0, int r, int h2) {
;     ...
;         if (need_mask) {
;             asm volatile("" ::: "memory");
;             const int lim = Q0 + r - key0 - 4 * h2;
; #pragma unroll
;             for (int kb = 0; kb < 2; ++kb)
; #pragma unroll
;                 for (int pq = 0; pq < 8; ++pq) { const int ko = 32 * kb + ((2 * pq) & 3) + 8 * ((2 * pq) >> 2); if (ko >= lim) kp[kb][pq].x = 1.f; if (ko + 1 >= lim) kp[kb][pq].y = 1.f; }
;         }
	v_add_u32_e32 v3, s74, v191
	v_or_b32_e32 v39, s12, v206
	v_sub_u32_e32 v3, v3, v39
	v_cmp_lt_i32_e32 vcc, 0, v3
	v_cmp_lt_i32_e64 s[20:21], 1, v3
	s_or_b64 vcc, s[20:21], vcc
	v_cndmask_b32_e32 v56, 1.0, v56, vcc
	v_cndmask_b32_e64 v57, 1.0, v57, s[20:21]
	v_cmp_lt_i32_e32 vcc, 2, v3
	v_cmp_lt_i32_e64 s[20:21], 3, v3
	s_or_b64 vcc, s[20:21], vcc
	v_cndmask_b32_e32 v4, 1.0, v4, vcc
	v_cndmask_b32_e64 v5, 1.0, v5, s[20:21]
	v_cmp_lt_i32_e32 vcc, 8, v3
	v_cmp_lt_i32_e64 s[20:21], 9, v3
	s_or_b64 vcc, s[20:21], vcc
	v_cndmask_b32_e32 v216, 1.0, v216, vcc
	v_cndmask_b32_e64 v217, 1.0, v217, s[20:21]
	v_cmp_lt_i32_e32 vcc, 10, v3
	v_cmp_lt_i32_e64 s[20:21], 11, v3
	s_or_b64 vcc, s[20:21], vcc
	v_cndmask_b32_e32 v62, 1.0, v62, vcc
	v_cndmask_b32_e64 v63, 1.0, v63, s[20:21]
	v_cmp_lt_i32_e32 vcc, 16, v3
	v_cmp_lt_i32_e64 s[20:21], 17, v3
	s_or_b64 vcc, s[20:21], vcc
	v_cndmask_b32_e32 v58, 1.0, v58, vcc
	v_cndmask_b32_e64 v59, 1.0, v59, s[20:21]
	v_cmp_lt_i32_e32 vcc, 18, v3
	v_cmp_lt_i32_e64 s[20:21], 19, v3
	s_or_b64 vcc, s[20:21], vcc
	v_cndmask_b32_e32 v60, 1.0, v60, vcc
	v_cndmask_b32_e64 v61, 1.0, v61, s[20:21]
	v_cmp_lt_i32_e32 vcc, 24, v3
	v_cmp_lt_i32_e64 s[20:21], 25, v3
	s_or_b64 vcc, s[20:21], vcc
	v_cndmask_b32_e32 v64, 1.0, v64, vcc
	v_cndmask_b32_e64 v65, 1.0, v65, s[20:21]
	v_cmp_lt_i32_e32 vcc, 26, v3
	v_cmp_lt_i32_e64 s[20:21], 27, v3
	s_or_b64 vcc, s[20:21], vcc
	v_cndmask_b32_e32 v66, 1.0, v66, vcc
	v_cndmask_b32_e64 v67, 1.0, v67, s[20:21]
	v_cmp_lt_i32_e32 vcc, 32, v3
	v_cmp_lt_i32_e64 s[20:21], 33, v3
	s_or_b64 vcc, s[20:21], vcc
	v_cndmask_b32_e32 v40, 1.0, v40, vcc
	v_cndmask_b32_e64 v41, 1.0, v41, s[20:21]
	v_cmp_lt_i32_e32 vcc, 34, v3
	v_cmp_lt_i32_e64 s[20:21], 35, v3
	s_or_b64 vcc, s[20:21], vcc
	v_cndmask_b32_e32 v42, 1.0, v42, vcc
	v_cndmask_b32_e64 v43, 1.0, v43, s[20:21]
	v_cmp_lt_i32_e32 vcc, 40, v3
	v_cmp_lt_i32_e64 s[20:21], 41, v3
	s_or_b64 vcc, s[20:21], vcc
	v_cndmask_b32_e32 v68, 1.0, v68, vcc
	v_cndmask_b32_e64 v69, 1.0, v69, s[20:21]
	v_cmp_lt_i32_e32 vcc, 42, v3
	v_cmp_lt_i32_e64 s[20:21], 43, v3
	s_or_b64 vcc, s[20:21], vcc
	v_cndmask_b32_e32 v70, 1.0, v70, vcc
	v_cndmask_b32_e64 v71, 1.0, v71, s[20:21]
	v_cmp_lt_i32_e32 vcc, 48, v3
	v_cmp_lt_i32_e64 s[20:21], 49, v3
	s_or_b64 vcc, s[20:21], vcc
	v_cndmask_b32_e32 v44, 1.0, v44, vcc
	v_cndmask_b32_e64 v45, 1.0, v45, s[20:21]
	v_cmp_lt_i32_e32 vcc, 50, v3
	v_cmp_lt_i32_e64 s[20:21], 51, v3
	s_or_b64 vcc, s[20:21], vcc
	v_cndmask_b32_e32 v46, 1.0, v46, vcc
	v_cndmask_b32_e64 v47, 1.0, v47, s[20:21]
	v_cmp_lt_i32_e32 vcc, 56, v3
	v_cmp_lt_i32_e64 s[20:21], 57, v3
	s_or_b64 vcc, s[20:21], vcc
	v_cndmask_b32_e32 v48, 1.0, v48, vcc
	v_cndmask_b32_e64 v49, 1.0, v49, s[20:21]
	v_cmp_lt_i32_e32 vcc, 58, v3
	v_cmp_lt_i32_e64 s[20:21], 59, v3
	s_or_b64 vcc, s[20:21], vcc
	v_cndmask_b32_e32 v50, 1.0, v50, vcc
	v_cndmask_b32_e64 v51, 1.0, v51, s[20:21]

; #define LAS __attribute__((address_space(3)))
; DI float fexp2(float x) { return __builtin_amdgcn_exp2f(x); }
; DI float frcp(float x) { return __builtin_amdgcn_rcpf(x); }
; #define MFMA32(a, b, c) __builtin_amdgcn_mfma_f32_32x32x16_bf16((a), (b), (c), 0, 0, 0)
; DI void prompt_tile(const LAS unsigned char* kc, const LAS unsigned char* vc, const bf16x8 (&qf)[4], f32x16 (&accO)[2], float& carry, float bias2, int key0, int Q0, int r, int h2) {
;     ...
;     if (key0 < Q0 + 31) {
;         f32x16 sk[2];
; #pragma unroll
;         for (int kb = 0; kb < 2; ++kb) {
; #pragma unroll
;             for (int i = 0; i < 16; ++i) sk[kb][i] = bias2;
; #pragma unroll
;             for (int s = 0; s < 4; ++s) { const bf16x8 a = *(const LAS bf16x8*)(kc + (32 * kb + r) * (KLD * 2) + (16 * s + 8 * h2) * 2); sk[kb] = MFMA32(a, qf[s], sk[kb]); }
;         }
;         const bool need_mask = key0 + 63 >= Q0;
;         f32x2 kp[2][8];
; #pragma unroll
;         for (int kb = 0; kb < 2; ++kb)
; #pragma unroll
;             for (int pq = 0; pq < 8; ++pq) {
;                 f32x2 e2; e2.x = fexp2(sk[kb][2 * pq]); e2.y = fexp2(sk[kb][2 * pq + 1]);
;                 const f32x2 d2 = e2 + 1.0f;
;                 f32x2 k2; k2.x = frcp(d2.x); k2.y = frcp(d2.y);
;                 kp[kb][pq] = k2;
;             }
.LBB0_633:
	s_max_i32 s16, s75, 2
	s_lshl_b32 s16, s16, 6
	s_addk_i32 s16, 0xff80
	s_ashr_i32 s17, s16, 31
	s_lshl_b64 s[18:19], s[16:17], 10
	v_lshl_add_u64 v[4:5], v[208:209], 0, s[18:19]
	global_load_dwordx4 v[168:171], v[4:5], off
	v_lshl_add_u64 v[4:5], s[16:17], 1, v[210:211]
	global_load_dwordx4 v[172:175], v[4:5], off
	v_cndmask_b32_e64 v3, 0, 1, s[12:13]
	v_cmp_ne_u32_e64 s[18:19], 1, v3
	s_andn2_b64 vcc, exec, s[12:13]
	s_cbranch_vccnz .LBB0_646
	s_lshl_b32 s12, s75, 6
	s_add_i32 s13, s74, 31
	v_readlane_b32 s16, v243, 24
	s_cmp_ge_i32 s12, s13
	v_readlane_b32 s17, v243, 25
	s_cbranch_scc1 .LBB0_638
	s_mul_i32 s13, s2, 0x2400
	v_add3_u32 v3, v218, s13, v219
	ds_read_b128 v[224:227], v3
	ds_read_b128 v[228:231], v3 offset:32
	v_mov_b32_e32 v39, v38
	v_mov_b64_e32 v[40:41], v[38:39]
	v_mov_b64_e32 v[42:43], v[38:39]
	v_mov_b64_e32 v[44:45], v[38:39]
	v_mov_b64_e32 v[46:47], v[38:39]
	v_mov_b64_e32 v[48:49], v[38:39]
	v_mov_b64_e32 v[50:51], v[38:39]
	v_mov_b64_e32 v[52:53], v[38:39]
	v_mov_b64_e32 v[54:55], v[38:39]
	s_or_b32 s13, s12, 63
	s_cmp_lt_i32 s13, s74
	s_waitcnt lgkmcnt(1)
	v_mfma_f32_32x32x16_bf16 v[56:71], v[224:227], v[72:75], v[40:55]
	ds_read_b128 v[224:227], v3 offset:64
	s_waitcnt lgkmcnt(1)
	v_mfma_f32_32x32x16_bf16 v[56:71], v[228:231], v[84:87], v[56:71]
	s_waitcnt lgkmcnt(0)
	v_mfma_f32_32x32x16_bf16 v[56:71], v[224:227], v[80:83], v[56:71]
	ds_read_b128 v[224:227], v3 offset:96
	s_waitcnt lgkmcnt(0)
	v_mfma_f32_32x32x16_bf16 v[56:71], v[224:227], v[76:79], v[56:71]
	ds_read_b128 v[224:227], v3 offset:4608
	s_waitcnt lgkmcnt(0)
	v_mfma_f32_32x32x16_bf16 v[40:55], v[224:227], v[72:75], v[40:55]
	ds_read_b128 v[224:227], v3 offset:4640
	s_nop 7
	v_exp_f32_e32 v4, v56
	v_exp_f32_e32 v5, v57
	s_nop 0
	v_pk_add_f32 v[4:5], v[4:5], 1.0 op_sel_hi:[1,0]
	s_waitcnt lgkmcnt(0)
	v_mfma_f32_32x32x16_bf16 v[40:55], v[224:227], v[84:87], v[40:55]
	ds_read_b128 v[224:227], v3 offset:4672
	v_rcp_f32_e32 v56, v4
	v_rcp_f32_e32 v57, v5
	v_exp_f32_e32 v4, v58
	v_exp_f32_e32 v5, v59
	v_exp_f32_e32 v58, v60
	v_exp_f32_e32 v59, v61
	s_waitcnt lgkmcnt(0)
	v_mfma_f32_32x32x16_bf16 v[40:55], v[224:227], v[80:83], v[40:55]
	ds_read_b128 v[224:227], v3 offset:4704
	v_add_f32_e64 v58, v58, 1.0
	v_add_f32_e64 v59, v59, 1.0
	v_exp_f32_e32 v60, v66
	v_rcp_f32_e32 v216, v58
	v_rcp_f32_e32 v217, v59
	v_exp_f32_e32 v58, v62
	v_exp_f32_e32 v59, v63
	s_waitcnt lgkmcnt(0)
	v_mfma_f32_32x32x16_bf16 v[40:55], v[224:227], v[76:79], v[40:55]
	v_add_f32_e64 v58, v58, 1.0
	v_add_f32_e64 v59, v59, 1.0
	v_exp_f32_e32 v61, v67
	v_rcp_f32_e32 v62, v58
	v_rcp_f32_e32 v63, v59
	v_exp_f32_e32 v58, v64
	v_exp_f32_e32 v59, v65
	v_exp_f32_e32 v64, v68
	s_nop 3
	v_exp_f32_e32 v44, v44
	v_exp_f32_e32 v45, v45
	v_exp_f32_e32 v65, v69
	v_exp_f32_e32 v66, v70
	v_exp_f32_e32 v67, v71
	v_pk_add_f32 v[44:45], v[44:45], 1.0 op_sel_hi:[1,0]
	v_exp_f32_e32 v40, v40
	v_rcp_f32_e32 v68, v44
	v_rcp_f32_e32 v69, v45
	v_exp_f32_e32 v44, v46
	v_exp_f32_e32 v45, v47
	v_exp_f32_e32 v41, v41
	v_exp_f32_e32 v42, v42
	v_exp_f32_e32 v43, v43
	v_pk_add_f32 v[44:45], v[44:45], 1.0 op_sel_hi:[1,0]
	v_exp_f32_e32 v46, v50
	v_rcp_f32_e32 v70, v44
	v_rcp_f32_e32 v71, v45
	v_exp_f32_e32 v44, v48
	v_exp_f32_e32 v45, v49
	v_exp_f32_e32 v47, v51
	v_exp_f32_e32 v48, v52
	v_exp_f32_e32 v49, v53
	v_exp_f32_e32 v50, v54
	v_exp_f32_e32 v51, v55
	v_pk_add_f32 v[4:5], v[4:5], 1.0 op_sel_hi:[1,0]
	v_pk_add_f32 v[58:59], v[58:59], 1.0 op_sel_hi:[1,0]
	v_pk_add_f32 v[60:61], v[60:61], 1.0 op_sel_hi:[1,0]
	v_pk_add_f32 v[64:65], v[64:65], 1.0 op_sel_hi:[1,0]
	v_pk_add_f32 v[66:67], v[66:67], 1.0 op_sel_hi:[1,0]
	v_pk_add_f32 v[40:41], v[40:41], 1.0 op_sel_hi:[1,0]
	v_pk_add_f32 v[42:43], v[42:43], 1.0 op_sel_hi:[1,0]
	v_pk_add_f32 v[44:45], v[44:45], 1.0 op_sel_hi:[1,0]
	v_pk_add_f32 v[46:47], v[46:47], 1.0 op_sel_hi:[1,0]
	v_pk_add_f32 v[48:49], v[48:49], 1.0 op_sel_hi:[1,0]
	v_pk_add_f32 v[50:51], v[50:51], 1.0 op_sel_hi:[1,0]
	v_rcp_f32_e32 v4, v4
	v_rcp_f32_e32 v5, v5
	v_rcp_f32_e32 v58, v58
	v_rcp_f32_e32 v59, v59
	v_rcp_f32_e32 v60, v60
	v_rcp_f32_e32 v61, v61
	v_rcp_f32_e32 v64, v64
	v_rcp_f32_e32 v65, v65
	v_rcp_f32_e32 v66, v66
	v_rcp_f32_e32 v67, v67
	v_rcp_f32_e32 v40, v40
	v_rcp_f32_e32 v41, v41
	v_rcp_f32_e32 v42, v42
	v_rcp_f32_e32 v43, v43
	v_rcp_f32_e32 v44, v44
	v_rcp_f32_e32 v45, v45
	v_rcp_f32_e32 v46, v46
	v_rcp_f32_e32 v47, v47
	v_rcp_f32_e32 v48, v48
	v_rcp_f32_e32 v49, v49
	v_rcp_f32_e32 v50, v50
	v_rcp_f32_e32 v51, v51
	s_cbranch_scc1 .LBB0_637
; DI void prompt_tile(const LAS unsigned char* kc, const LAS unsigned char* vc, const bf16x8 (&qf)[4], f32x16 (&accO)[2], float& carry, float bias2, int key0, int Q0, int r, int h2) {
;     ...
;         if (need_mask) {
;             asm volatile("" ::: "memory");
;             const int lim = Q0 + r - key0 - 4 * h2;
; #pragma unroll
;             for (int kb = 0; kb < 2; ++kb)
; #pragma unroll
;                 for (int pq = 0; pq < 8; ++pq) { const int ko = 32 * kb + ((2 * pq) & 3) + 8 * ((2 * pq) >> 2); if (ko >= lim) kp[kb][pq].x = 1.f; if (ko + 1 >= lim) kp[kb][pq].y = 1.f; }
;         }
	v_add_u32_e32 v3, s74, v191
	v_or_b32_e32 v39, s12, v206
	v_sub_u32_e32 v3, v3, v39
	v_cmp_lt_i32_e32 vcc, 0, v3
	v_cmp_lt_i32_e64 s[20:21], 1, v3
	s_or_b64 vcc, s[20:21], vcc
	v_cndmask_b32_e32 v56, 1.0, v56, vcc
	v_cndmask_b32_e64 v57, 1.0, v57, s[20:21]
	v_cmp_lt_i32_e32 vcc, 2, v3
	v_cmp_lt_i32_e64 s[20:21], 3, v3
	s_or_b64 vcc, s[20:21], vcc
	v_cndmask_b32_e32 v4, 1.0, v4, vcc
	v_cndmask_b32_e64 v5, 1.0, v5, s[20:21]
	v_cmp_lt_i32_e32 vcc, 8, v3
	v_cmp_lt_i32_e64 s[20:21], 9, v3
	s_or_b64 vcc, s[20:21], vcc
	v_cndmask_b32_e32 v216, 1.0, v216, vcc
	v_cndmask_b32_e64 v217, 1.0, v217, s[20:21]
	v_cmp_lt_i32_e32 vcc, 10, v3
	v_cmp_lt_i32_e64 s[20:21], 11, v3
	s_or_b64 vcc, s[20:21], vcc
	v_cndmask_b32_e32 v62, 1.0, v62, vcc
	v_cndmask_b32_e64 v63, 1.0, v63, s[20:21]
	v_cmp_lt_i32_e32 vcc, 16, v3
	v_cmp_lt_i32_e64 s[20:21], 17, v3
	s_or_b64 vcc, s[20:21], vcc
	v_cndmask_b32_e32 v58, 1.0, v58, vcc
	v_cndmask_b32_e64 v59, 1.0, v59, s[20:21]
	v_cmp_lt_i32_e32 vcc, 18, v3
	v_cmp_lt_i32_e64 s[20:21], 19, v3
	s_or_b64 vcc, s[20:21], vcc
	v_cndmask_b32_e32 v60, 1.0, v60, vcc
	v_cndmask_b32_e64 v61, 1.0, v61, s[20:21]
	v_cmp_lt_i32_e32 vcc, 24, v3
	v_cmp_lt_i32_e64 s[20:21], 25, v3
	s_or_b64 vcc, s[20:21], vcc
	v_cndmask_b32_e32 v64, 1.0, v64, vcc
	v_cndmask_b32_e64 v65, 1.0, v65, s[20:21]
	v_cmp_lt_i32_e32 vcc, 26, v3
	v_cmp_lt_i32_e64 s[20:21], 27, v3
	s_or_b64 vcc, s[20:21], vcc
	v_cndmask_b32_e32 v66, 1.0, v66, vcc
	v_cndmask_b32_e64 v67, 1.0, v67, s[20:21]
	v_cmp_lt_i32_e32 vcc, 32, v3
	v_cmp_lt_i32_e64 s[20:21], 33, v3
	s_or_b64 vcc, s[20:21], vcc
	v_cndmask_b32_e32 v40, 1.0, v40, vcc
	v_cndmask_b32_e64 v41, 1.0, v41, s[20:21]
	v_cmp_lt_i32_e32 vcc, 34, v3
	v_cmp_lt_i32_e64 s[20:21], 35, v3
	s_or_b64 vcc, s[20:21], vcc
	v_cndmask_b32_e32 v42, 1.0, v42, vcc
	v_cndmask_b32_e64 v43, 1.0, v43, s[20:21]
	v_cmp_lt_i32_e32 vcc, 40, v3
	v_cmp_lt_i32_e64 s[20:21], 41, v3
	s_or_b64 vcc, s[20:21], vcc
	v_cndmask_b32_e32 v68, 1.0, v68, vcc
	v_cndmask_b32_e64 v69, 1.0, v69, s[20:21]
	v_cmp_lt_i32_e32 vcc, 42, v3
	v_cmp_lt_i32_e64 s[20:21], 43, v3
	s_or_b64 vcc, s[20:21], vcc
	v_cndmask_b32_e32 v70, 1.0, v70, vcc
	v_cndmask_b32_e64 v71, 1.0, v71, s[20:21]
	v_cmp_lt_i32_e32 vcc, 48, v3
	v_cmp_lt_i32_e64 s[20:21], 49, v3
	s_or_b64 vcc, s[20:21], vcc
	v_cndmask_b32_e32 v44, 1.0, v44, vcc
	v_cndmask_b32_e64 v45, 1.0, v45, s[20:21]
	v_cmp_lt_i32_e32 vcc, 50, v3
	v_cmp_lt_i32_e64 s[20:21], 51, v3
	s_or_b64 vcc, s[20:21], vcc
	v_cndmask_b32_e32 v46, 1.0, v46, vcc
	v_cndmask_b32_e64 v47, 1.0, v47, s[20:21]
	v_cmp_lt_i32_e32 vcc, 56, v3
	v_cmp_lt_i32_e64 s[20:21], 57, v3
	s_or_b64 vcc, s[20:21], vcc
	v_cndmask_b32_e32 v48, 1.0, v48, vcc
	v_cndmask_b32_e64 v49, 1.0, v49, s[20:21]
	v_cmp_lt_i32_e32 vcc, 58, v3
	v_cmp_lt_i32_e64 s[20:21], 59, v3
	s_or_b64 vcc, s[20:21], vcc
	v_cndmask_b32_e32 v50, 1.0, v50, vcc
	v_cndmask_b32_e64 v51, 1.0, v51, s[20:21]
